# scan: half of the state-update transposed fragment reads hoisted between the two G tiles
# baseline (speedup 1.0000x reference)
; #define LAS __attribute__((address_space(3)))
; template <bool DRY>
; __device__ __forceinline__ void ssd_chunk(SsdRegs& R, f32x4 (&st)[2], LAS unsigned char* L, bf16_t* BIG, const float* DT, float* SSQY, const SsdItem& I, int c, int tid, int lane, int wave, int li, int pi, int c16, int q4) {
;     ...
; #pragma unroll
;         for (int t = 0; t < 2; ++t) {
;             const int si = 2 * pi + t;
;             u32x2 w; w.x = 0u; w.y = 0u;
;             if (si <= li) {
;                 f32x4 d = (f32x4){0.f, 0.f, 0.f, 0.f};
; #pragma unroll
;                 for (int kk = 0; kk < 4; ++kk) d = __builtin_amdgcn_mfma_f32_16x16x32_bf16(SSD_FRAG(BS, PC, 16 * si, kk), cfr[kk], d, 0, 0, 0);
;                 float gv[4];
;                 const f32x4 acs_s = *(const LAS f32x4*)(SCW + (16 * si + 4 * q4) * 4), dt_s = *(const LAS f32x4*)(SCW + 256 + (16 * si + 4 * q4) * 4);
; #pragma unroll
;                 for (int e = 0; e < 4; ++e) gv[e] = d[e] * __expf(acs_l - acs_s[e]) * dt_s[e];
;                 if (si == li) {
; #pragma unroll
;                     for (int e = 0; e < 4; ++e) gv[e] = (4 * q4 + e <= c16) ? gv[e] : 0.f;
;                 }
;                 w.x = pk2(gv[0], gv[1]); w.y = pk2(gv[2], gv[3]);
;             }
;             *(LAS u32x2*)(L + GG + l * PT + (16 * si + 4 * q4) * 2) = w;
;         }
;     }
;     f32x4 stn[2];
;     bf16x8 xfr[2][2], bwf[2];
; #pragma unroll
;     for (int kk = 0; kk < 2; ++kk) { bwf[kk] = SSD_TR(BW, PB, trB, wave, kk); xfr[0][kk] = SSD_TR(XI, PX, trX, 0, kk); xfr[1][kk] = SSD_TR(XI, PX, trX, 1, kk); }
; #pragma unroll
;     for (int pt = 0; pt < 2; ++pt) {
;         f32x4 d = st[pt] * etot;
; #pragma unroll
;         for (int kk = 0; kk < 2; ++kk) d = __builtin_amdgcn_mfma_f32_16x16x32_bf16(bwf[kk], xfr[pt][kk], d, 0, 0, 0);
;         stn[pt] = d;
;     }
;     const bf16x8 xy0 = pi ? xfr[1][0] : xfr[0][0], xy1 = pi ? xfr[1][1] : xfr[0][1];
;     st[0] = stn[0]; st[1] = stn[1];
;     __syncthreads();
;     {
;         f32x4 d1 = (f32x4){0.f, 0.f, 0.f, 0.f}, d2 = (f32x4){0.f, 0.f, 0.f, 0.f};
; #pragma unroll
;         for (int kk = 0; kk < 2; ++kk) d1 = __builtin_amdgcn_mfma_f32_16x16x32_bf16(kk ? xy1 : xy0, SSD_FRAG(GG, PT, 16 * li, kk), d1, 0, 0, 0);
; #pragma unroll
;         for (int kk = 0; kk < 4; ++kk) d2 = __builtin_amdgcn_mfma_f32_16x16x32_bf16(SSD_FRAG(SB, PC, 16 * pi, kk), cfr[kk], d2, 0, 0, 0);
.LBB0_729:
	v_add_u32_e32 v144, s68, v113
	ds_write_b64 v144, v[106:107]
	ds_read_b64_tr_b16 v[176:177], v194 offset:17408
	ds_read_b64_tr_b16 v[178:179], v194 offset:18496
	ds_read_b64_tr_b16 v[152:153], v138 offset:35200
	ds_read_b64_tr_b16 v[150:151], v138 offset:34816
	ds_read_b64_tr_b16 v[162:163], v138 offset:34848
	ds_read_b64_tr_b16 v[164:165], v138 offset:35232
	ds_read_b64_tr_b16 v[180:181], v194 offset:26112
	ds_read_b64_tr_b16 v[182:183], v194 offset:27200
	s_not_b64 s[24:25], s[84:85]
	s_andn2_b64 vcc, exec, s[84:85]
	s_mov_b64 s[0:1], -1
	s_cbranch_vccnz .LBB0_731
	s_mov_b64 s[0:1], 0
.LBB0_731:
	v_mov_b32_e32 v106, 0
	s_andn2_b64 vcc, exec, s[0:1]
	v_mov_b32_e32 v107, 0
	s_cbranch_vccnz .LBB0_733
	s_waitcnt lgkmcnt(14)
	v_mfma_f32_16x16x32_bf16 v[146:149], v[220:223], v[70:73], 0
	s_waitcnt lgkmcnt(13)
	v_mfma_f32_16x16x32_bf16 v[146:149], v[224:227], v[66:69], v[146:149]
	s_waitcnt lgkmcnt(12)
	v_mfma_f32_16x16x32_bf16 v[146:149], v[228:231], v[62:65], v[146:149]
	s_waitcnt lgkmcnt(11)
	v_mfma_f32_16x16x32_bf16 v[146:149], v[232:235], v[58:61], v[146:149]
	s_waitcnt lgkmcnt(10)
	v_sub_f32_e32 v106, v76, v236
	v_sub_f32_e32 v107, v76, v237
	v_exp_f32_e32 v106, v106
	v_exp_f32_e32 v107, v107
	v_sub_f32_e32 v143, v76, v238
	v_sub_f32_e32 v76, v76, v239
	v_pk_mul_f32 v[106:107], v[146:147], v[106:107]
	v_exp_f32_e32 v146, v143
	v_exp_f32_e32 v147, v76
	s_waitcnt lgkmcnt(9)
	v_pk_mul_f32 v[106:107], v[188:189], v[106:107]
	v_pk_mul_f32 v[146:147], v[148:149], v[146:147]
	s_nop 0
	v_pk_mul_f32 v[146:147], v[190:191], v[146:147]
	v_cndmask_b32_e64 v76, v106, 0, s[6:7]
	v_cndmask_b32_e64 v143, 0, v107, s[8:9]
	v_cndmask_b32_e64 v145, v146, 0, s[10:11]
	v_cndmask_b32_e64 v148, v147, 0, s[12:13]
	v_cndmask_b32_e64 v76, v106, v76, s[14:15]
	v_cndmask_b32_e64 v106, v107, v143, s[14:15]
	v_cndmask_b32_e64 v145, v146, v145, s[14:15]
	v_cndmask_b32_e64 v146, v147, v148, s[14:15]
	v_cvt_pk_bf16_f32 v106, v76, v106
	v_cvt_pk_bf16_f32 v107, v145, v146
.LBB0_733:
	v_add_u32_e32 v145, s69, v113
	s_waitcnt lgkmcnt(9)
	ds_write_b64 v145, v[106:107]
	v_exp_f32_e32 v76, s3
	ds_read_b64_tr_b16 v[158:159], v138 offset:37888
	ds_read_b64_tr_b16 v[160:161], v138 offset:38272
	ds_read_b64_tr_b16 v[166:167], v138 offset:37920
	ds_read_b64_tr_b16 v[168:169], v138 offset:38304
	v_pk_mul_f32 v[52:53], v[52:53], v[76:77] op_sel_hi:[1,0]
	v_pk_mul_f32 v[50:51], v[50:51], v[76:77] op_sel_hi:[1,0]
	v_pk_mul_f32 v[56:57], v[56:57], v[76:77] op_sel_hi:[1,0]
	v_pk_mul_f32 v[54:55], v[54:55], v[76:77] op_sel_hi:[1,0]
	s_waitcnt lgkmcnt(5)
	v_mfma_f32_16x16x32_bf16 v[50:53], v[176:179], v[150:153], v[50:53]
	ds_read_b64_tr_b16 v[196:197], v83 offset:53248
	ds_read_b64_tr_b16 v[198:199], v83 offset:53632
	ds_read_b64_tr_b16 v[200:201], v83 offset:56320
	ds_read_b64_tr_b16 v[202:203], v83 offset:56704
	v_add_u32_e32 v143, v112, v111
	s_waitcnt lgkmcnt(0)
	s_barrier
	v_mfma_f32_16x16x32_bf16 v[54:57], v[176:179], v[162:165], v[54:57]
	v_mfma_f32_16x16x32_bf16 v[50:53], v[180:183], v[158:161], v[50:53]
	v_mfma_f32_16x16x32_bf16 v[54:57], v[180:183], v[166:169], v[54:57]
	ds_read_b128 v[150:153], v143
	ds_read_b128 v[154:157], v123
	ds_read_b32 v76, v132
	s_waitcnt lgkmcnt(2)
	v_mfma_f32_16x16x32_bf16 v[146:149], v[196:199], v[150:153], 0
	ds_read_b128 v[150:153], v123 offset:64
	s_waitcnt lgkmcnt(2)
	v_mfma_f32_16x16x32_bf16 v[70:73], v[154:157], v[70:73], 0
	ds_read_b128 v[154:157], v123 offset:128
	s_waitcnt lgkmcnt(1)
	v_mfma_f32_16x16x32_bf16 v[66:69], v[150:153], v[66:69], v[70:73]
	s_nop 4
	ds_read_b128 v[70:73], v123 offset:192
	s_waitcnt lgkmcnt(1)
	v_mfma_f32_16x16x32_bf16 v[62:65], v[154:157], v[62:65], v[66:69]
	s_nop 2
	ds_read_b128 v[66:69], v143 offset:64
	s_waitcnt lgkmcnt(1)
	v_mfma_f32_16x16x32_bf16 v[58:61], v[70:73], v[58:61], v[62:65]
	v_lshlrev_b32_e32 v70, 16, v96
	s_nop 1
	v_exp_f32_e32 v72, v76
	v_mul_f32_e32 v62, 0xbfb8aa3b, v70
	v_exp_f32_e32 v71, v62
	s_waitcnt lgkmcnt(0)
	v_mfma_f32_16x16x32_bf16 v[62:65], v[200:203], v[66:69], v[146:149]
	ds_read_b64 v[66:67], v139 offset:53248
	s_nop 6
	v_fma_f32 v62, v58, v72, v62
	v_add_f32_e32 v58, 1.0, v71
	v_rcp_f32_e32 v76, v58
	v_and_b32_e32 v58, 0xffff0000, v96
	v_mul_f32_e32 v68, 0xbfb8aa3b, v58
	v_exp_f32_e32 v73, v68
	s_waitcnt lgkmcnt(0)
	v_lshlrev_b32_e32 v71, 16, v66
	v_pk_mul_f32 v[68:69], v[76:77], v[70:71]
	v_fma_f32 v63, v59, v72, v63
	v_add_f32_e32 v62, v62, v69
	v_add_f32_e32 v69, 1.0, v73
	v_rcp_f32_e32 v76, v69
	v_and_b32_e32 v59, 0xffff0000, v66
	v_mul_f32_e32 v62, v68, v62
	v_fma_f32 v64, v60, v72, v64
	v_pk_mul_f32 v[58:59], v[76:77], v[58:59]
	v_fmac_f32_e32 v65, v61, v72
	v_add_f32_e32 v59, v63, v59
	v_mul_f32_e32 v63, v58, v59
	v_lshlrev_b32_e32 v58, 16, v97
	v_mul_f32_e32 v59, 0xbfb8aa3b, v58
	v_exp_f32_e32 v68, v59
	v_lshlrev_b32_e32 v59, 16, v67
	v_and_b32_e32 v61, 0xffff0000, v67
	v_mul_f32_e32 v66, v63, v63
	v_add_f32_e32 v60, 1.0, v68
	v_rcp_f32_e32 v76, v60
	v_and_b32_e32 v60, 0xffff0000, v97
	v_mul_f32_e32 v68, 0xbfb8aa3b, v60
	v_exp_f32_e32 v68, v68
	v_pk_mul_f32 v[58:59], v[76:77], v[58:59]
	v_fmac_f32_e32 v66, v62, v62
	v_add_f32_e32 v59, v64, v59
	v_mul_f32_e32 v64, v58, v59
	v_add_f32_e32 v58, 1.0, v68
	v_rcp_f32_e32 v76, v58
	v_fmac_f32_e32 v66, v64, v64
	v_pk_mul_f32 v[58:59], v[76:77], v[60:61]
	s_nop 0
	v_add_f32_e32 v59, v65, v59
	v_mul_f32_e32 v58, v58, v59
	v_fmac_f32_e32 v66, v58, v58
	v_mov_b32_e32 v59, v66
	v_cvt_pk_bf16_f32 v60, v62, v63
	v_cvt_pk_bf16_f32 v61, v64, v58
	v_permlane16_swap_b32 v59, v66
	global_store_dwordx2 v[78:79], v[60:61], off
	v_add_f32_e32 v58, v66, v59
	v_mov_b32_e32 v59, v58
	s_mov_b64 s[0:1], 0xc0000
	v_lshl_add_u64 v[78:79], v[78:79], 0, s[0:1]
	s_nop 0
	v_permlane32_swap_b32 v59, v58
	s_and_saveexec_b64 s[0:1], s[18:19]
	s_cbranch_execz .LBB0_735
	v_add_f32_e32 v60, v58, v59
	global_store_dword v[90:91], v60, off

; #define LAS __attribute__((address_space(3)))
; template <bool DRY>
; __device__ __forceinline__ void ssd_chunk(SsdRegs& R, f32x4 (&st)[2], LAS unsigned char* L, bf16_t* BIG, const float* DT, float* SSQY, const SsdItem& I, int c, int tid, int lane, int wave, int li, int pi, int c16, int q4) {
;     ...
; #pragma unroll
;         for (int t = 0; t < 2; ++t) {
;             const int si = 2 * pi + t;
;             u32x2 w; w.x = 0u; w.y = 0u;
;             if (si <= li) {
;                 f32x4 d = (f32x4){0.f, 0.f, 0.f, 0.f};
; #pragma unroll
;                 for (int kk = 0; kk < 4; ++kk) d = __builtin_amdgcn_mfma_f32_16x16x32_bf16(SSD_FRAG(BS, PC, 16 * si, kk), cfr[kk], d, 0, 0, 0);
;                 float gv[4];
;                 const f32x4 acs_s = *(const LAS f32x4*)(SCW + (16 * si + 4 * q4) * 4), dt_s = *(const LAS f32x4*)(SCW + 256 + (16 * si + 4 * q4) * 4);
; #pragma unroll
;                 for (int e = 0; e < 4; ++e) gv[e] = d[e] * __expf(acs_l - acs_s[e]) * dt_s[e];
;                 if (si == li) {
; #pragma unroll
;                     for (int e = 0; e < 4; ++e) gv[e] = (4 * q4 + e <= c16) ? gv[e] : 0.f;
;                 }
;                 w.x = pk2(gv[0], gv[1]); w.y = pk2(gv[2], gv[3]);
;             }
;             *(LAS u32x2*)(L + GG + l * PT + (16 * si + 4 * q4) * 2) = w;
;         }
;     }
;     f32x4 stn[2];
;     bf16x8 xfr[2][2], bwf[2];
; #pragma unroll
;     for (int kk = 0; kk < 2; ++kk) { bwf[kk] = SSD_TR(BW, PB, trB, wave, kk); xfr[0][kk] = SSD_TR(XI, PX, trX, 0, kk); xfr[1][kk] = SSD_TR(XI, PX, trX, 1, kk); }
; #pragma unroll
;     for (int pt = 0; pt < 2; ++pt) {
;         f32x4 d = st[pt] * etot;
; #pragma unroll
;         for (int kk = 0; kk < 2; ++kk) d = __builtin_amdgcn_mfma_f32_16x16x32_bf16(bwf[kk], xfr[pt][kk], d, 0, 0, 0);
;         stn[pt] = d;
;     }
;     const bf16x8 xy0 = pi ? xfr[1][0] : xfr[0][0], xy1 = pi ? xfr[1][1] : xfr[0][1];
;     st[0] = stn[0]; st[1] = stn[1];
;     __syncthreads();
;     {
;         f32x4 d1 = (f32x4){0.f, 0.f, 0.f, 0.f}, d2 = (f32x4){0.f, 0.f, 0.f, 0.f};
; #pragma unroll
;         for (int kk = 0; kk < 2; ++kk) d1 = __builtin_amdgcn_mfma_f32_16x16x32_bf16(kk ? xy1 : xy0, SSD_FRAG(GG, PT, 16 * li, kk), d1, 0, 0, 0);
; #pragma unroll
;         for (int kk = 0; kk < 4; ++kk) d2 = __builtin_amdgcn_mfma_f32_16x16x32_bf16(SSD_FRAG(SB, PC, 16 * pi, kk), cfr[kk], d2, 0, 0, 0);
.LBB0_744:
	ds_read_b64_tr_b16 v[176:177], v194 offset:17408
	ds_read_b64_tr_b16 v[178:179], v194 offset:18496
	ds_read_b64_tr_b16 v[150:151], v138 offset:35200
	ds_read_b64_tr_b16 v[148:149], v138 offset:34816
	ds_read_b64_tr_b16 v[162:163], v138 offset:35232
	ds_read_b64_tr_b16 v[160:161], v138 offset:34848
	ds_read_b64_tr_b16 v[180:181], v194 offset:26112
	ds_read_b64_tr_b16 v[182:183], v194 offset:27200
	v_mov_b32_e32 v100, 0
	s_andn2_b64 vcc, exec, s[0:1]
	v_mov_b32_e32 v101, 0
	s_cbranch_vccnz .LBB0_746
.LBB0_745:
	s_waitcnt lgkmcnt(14)
	v_mfma_f32_16x16x32_bf16 v[100:103], v[220:223], v[70:73], 0
	s_waitcnt lgkmcnt(13)
	v_mfma_f32_16x16x32_bf16 v[100:103], v[224:227], v[66:69], v[100:103]
	s_waitcnt lgkmcnt(12)
	v_mfma_f32_16x16x32_bf16 v[100:103], v[228:231], v[62:65], v[100:103]
	s_waitcnt lgkmcnt(11)
	v_mfma_f32_16x16x32_bf16 v[100:103], v[232:235], v[58:61], v[100:103]
	s_nop 1
	s_waitcnt lgkmcnt(10)
	v_sub_f32_e32 v104, v76, v236
	v_sub_f32_e32 v105, v76, v237
	v_exp_f32_e32 v104, v104
	v_exp_f32_e32 v105, v105
	s_nop 0
	v_pk_mul_f32 v[100:101], v[100:101], v[104:105]
	v_sub_f32_e32 v104, v76, v238
	v_sub_f32_e32 v76, v76, v239
	v_exp_f32_e32 v104, v104
	v_exp_f32_e32 v105, v76
	s_waitcnt lgkmcnt(9)
	v_pk_mul_f32 v[100:101], v[188:189], v[100:101]
	v_pk_mul_f32 v[102:103], v[102:103], v[104:105]
	s_nop 0
	v_pk_mul_f32 v[102:103], v[190:191], v[102:103]
	v_cndmask_b32_e64 v76, v100, 0, s[6:7]
	v_cndmask_b32_e64 v104, 0, v101, s[8:9]
	v_cndmask_b32_e64 v105, v102, 0, s[10:11]
	v_cndmask_b32_e64 v142, v103, 0, s[12:13]
	v_cndmask_b32_e64 v76, v100, v76, s[14:15]
	v_cndmask_b32_e64 v100, v101, v104, s[14:15]
	v_cndmask_b32_e64 v102, v102, v105, s[14:15]
	v_cndmask_b32_e64 v103, v103, v142, s[14:15]
	v_cvt_pk_bf16_f32 v100, v76, v100
	v_cvt_pk_bf16_f32 v101, v102, v103
.LBB0_746:
	s_waitcnt lgkmcnt(9)
	v_exp_f32_e32 v76, s3
	ds_write_b64 v145, v[100:101]
	ds_read_b64_tr_b16 v[156:157], v138 offset:37888
	ds_read_b64_tr_b16 v[158:159], v138 offset:38272
	ds_read_b64_tr_b16 v[166:167], v138 offset:38304
	v_pk_mul_f32 v[52:53], v[52:53], v[76:77] op_sel_hi:[1,0]
	v_pk_mul_f32 v[50:51], v[50:51], v[76:77] op_sel_hi:[1,0]
	ds_read_b64_tr_b16 v[164:165], v138 offset:37920
	v_pk_mul_f32 v[56:57], v[56:57], v[76:77] op_sel_hi:[1,0]
	v_pk_mul_f32 v[54:55], v[54:55], v[76:77] op_sel_hi:[1,0]
	s_waitcnt lgkmcnt(5)
	v_mfma_f32_16x16x32_bf16 v[50:53], v[176:179], v[148:151], v[50:53]
	ds_read_b64_tr_b16 v[196:197], v83 offset:59392
	ds_read_b64_tr_b16 v[198:199], v83 offset:59776
	ds_read_b64_tr_b16 v[200:201], v83 offset:62464
	ds_read_b64_tr_b16 v[202:203], v83 offset:62848
	s_waitcnt lgkmcnt(0)
	s_barrier
	v_mfma_f32_16x16x32_bf16 v[54:57], v[176:179], v[160:163], v[54:57]
	v_mfma_f32_16x16x32_bf16 v[50:53], v[180:183], v[156:159], v[50:53]
	ds_read_b128 v[148:151], v143
	v_mfma_f32_16x16x32_bf16 v[54:57], v[180:183], v[164:167], v[54:57]
	ds_read_b128 v[152:155], v125
	s_waitcnt lgkmcnt(1)
	v_mfma_f32_16x16x32_bf16 v[100:103], v[196:199], v[148:151], 0
	ds_read_b128 v[148:151], v125 offset:64
	s_waitcnt lgkmcnt(1)
	v_mfma_f32_16x16x32_bf16 v[70:73], v[152:155], v[70:73], 0
	ds_read_b128 v[152:155], v125 offset:128
	s_waitcnt lgkmcnt(1)
	v_mfma_f32_16x16x32_bf16 v[66:69], v[148:151], v[66:69], v[70:73]
	s_nop 4
	ds_read_b128 v[70:73], v125 offset:192
	ds_read_b32 v76, v132
	s_waitcnt lgkmcnt(2)
	v_mfma_f32_16x16x32_bf16 v[62:65], v[152:155], v[62:65], v[66:69]
	s_nop 2
	v_lshlrev_b32_e32 v68, 16, v92
	s_waitcnt lgkmcnt(1)
	v_mfma_f32_16x16x32_bf16 v[58:61], v[70:73], v[58:61], v[62:65]
	v_mul_f32_e32 v69, 0xbfb8aa3b, v68
	v_exp_f32_e32 v69, v69
	s_waitcnt lgkmcnt(0)
	v_exp_f32_e32 v70, v76
	ds_read_b128 v[62:65], v143 offset:64
	ds_read_b64 v[66:67], v139 offset:59392
	s_waitcnt lgkmcnt(1)
	v_mfma_f32_16x16x32_bf16 v[62:65], v[200:203], v[62:65], v[100:103]
	s_nop 7
	v_fma_f32 v62, v58, v70, v62
	v_add_f32_e32 v58, 1.0, v69
	v_rcp_f32_e32 v76, v58
	v_and_b32_e32 v58, 0xffff0000, v92
	v_mul_f32_e32 v69, 0xbfb8aa3b, v58
	v_exp_f32_e32 v71, v69
	s_waitcnt lgkmcnt(0)
	v_lshlrev_b32_e32 v69, 16, v66
	v_pk_mul_f32 v[68:69], v[76:77], v[68:69]
	v_fma_f32 v63, v59, v70, v63
	v_add_f32_e32 v62, v62, v69
	v_add_f32_e32 v69, 1.0, v71
	v_rcp_f32_e32 v76, v69
	v_and_b32_e32 v59, 0xffff0000, v66
	v_mul_f32_e32 v62, v68, v62
	v_fma_f32 v64, v60, v70, v64
	v_pk_mul_f32 v[58:59], v[76:77], v[58:59]
	v_fmac_f32_e32 v65, v61, v70
	v_add_f32_e32 v59, v63, v59
	v_mul_f32_e32 v63, v58, v59
	v_lshlrev_b32_e32 v58, 16, v93
	v_mul_f32_e32 v59, 0xbfb8aa3b, v58
	v_exp_f32_e32 v68, v59
	v_lshlrev_b32_e32 v59, 16, v67
	v_and_b32_e32 v61, 0xffff0000, v67
	v_mul_f32_e32 v66, v63, v63
	v_add_f32_e32 v60, 1.0, v68
	v_rcp_f32_e32 v76, v60
	v_and_b32_e32 v60, 0xffff0000, v93
	v_mul_f32_e32 v68, 0xbfb8aa3b, v60
	v_exp_f32_e32 v68, v68
	v_pk_mul_f32 v[58:59], v[76:77], v[58:59]
	v_fmac_f32_e32 v66, v62, v62
	v_add_f32_e32 v59, v64, v59
	v_mul_f32_e32 v64, v58, v59
	v_add_f32_e32 v58, 1.0, v68
	v_rcp_f32_e32 v76, v58
	v_fmac_f32_e32 v66, v64, v64
	v_pk_mul_f32 v[58:59], v[76:77], v[60:61]
	s_nop 0
	v_add_f32_e32 v59, v65, v59
	v_mul_f32_e32 v58, v58, v59
	v_fmac_f32_e32 v66, v58, v58
	v_mov_b32_e32 v59, v66
	v_cvt_pk_bf16_f32 v60, v62, v63
	v_cvt_pk_bf16_f32 v61, v64, v58
	v_permlane16_swap_b32 v59, v66
	global_store_dwordx2 v[78:79], v[60:61], off
	v_add_f32_e32 v58, v66, v59
	v_mov_b32_e32 v59, v58
	s_mov_b64 s[0:1], 0xc0000
	v_lshl_add_u64 v[78:79], v[78:79], 0, s[0:1]
	s_nop 0
	v_permlane32_swap_b32 v59, v58
	s_and_saveexec_b64 s[0:1], s[18:19]
	s_cbranch_execz .LBB0_719
	v_add_f32_e32 v60, v58, v59
	global_store_dword v[90:91], v60, off offset:256
	s_branch .LBB0_719

; #define SSD_TR(base, pitch, troff, ct, kk) __builtin_shufflevector( \
;         __builtin_amdgcn_ds_read_tr16_b64_v4i16((LAS s16x4*)(L + (base) + (troff) + (kk) * 32 * (pitch) + (ct) * 32)), \
;         __builtin_amdgcn_ds_read_tr16_b64_v4i16((LAS s16x4*)(L + (base) + (troff) + (kk) * 32 * (pitch) + 4 * (pitch) + (ct) * 32)), 0, 1, 2, 3, 4, 5, 6, 7)
; template <bool DRY>
; __device__ __forceinline__ void ssd_chunk(SsdRegs& R, f32x4 (&st)[2], LAS unsigned char* L, bf16_t* BIG, const float* DT, float* SSQY, const SsdItem& I, int c, int tid, int lane, int wave, int li, int pi, int c16, int q4) {
;     ...
;     bf16x8 xfr[2][2], bwf[2];
; #pragma unroll
;     for (int kk = 0; kk < 2; ++kk) { bwf[kk] = SSD_TR(BW, PB, trB, wave, kk); xfr[0][kk] = SSD_TR(XI, PX, trX, 0, kk); xfr[1][kk] = SSD_TR(XI, PX, trX, 1, kk); }
.LBB0_749:
	ds_read_b64_tr_b16 v[176:177], v194 offset:17408
	ds_read_b64_tr_b16 v[178:179], v194 offset:18496
	ds_read_b64_tr_b16 v[150:151], v138 offset:35200
	ds_read_b64_tr_b16 v[148:149], v138 offset:34816
	ds_read_b64_tr_b16 v[162:163], v138 offset:35232
	ds_read_b64_tr_b16 v[160:161], v138 offset:34848
	ds_read_b64_tr_b16 v[180:181], v194 offset:26112
	ds_read_b64_tr_b16 v[182:183], v194 offset:27200
	v_mov_b32_e32 v100, 0
	v_mov_b32_e32 v101, 0
	s_cbranch_execz .LBB0_745
	s_branch .LBB0_746
